# E2A conv loop: prefetch distance 3 (unrolled x3, rotating buffers in VGPRs idle during the phase), on top of v42
# baseline (speedup 1.0000x reference)
; __device__ __forceinline__ float bflo(unsigned v) { return __uint_as_float(v << 16); }
; __device__ __forceinline__ float bfhi(unsigned v) { return __uint_as_float(v & 0xffff0000u); }
; __device__ __forceinline__ void conv_unit(const Params& p, const WS& ws, int j, int u) {
;     ...
;   bf16_t* xp = ws.XA + (size_t)(b * T_) * 1024 + cbase;
;   float x0[8], x1[8], x2[8];
;   {
;     u32x4 h[3];
; #pragma unroll
;     for (int m = 0; m < 3; ++m) {
;       const int t = t0 - 3 + m;
;       h[m] = (u32x4){0, 0, 0, 0};
;       if (t >= 0) h[m] = *(const u32x4*)(xp + (size_t)t * 1024);
;     }
;     const u32x4 a = h[0], bq = h[1], c = h[2];
;     x0[0] = bflo(a.x); x0[1] = bfhi(a.x); x0[2] = bflo(a.y); x0[3] = bfhi(a.y); x0[4] = bflo(a.z); x0[5] = bfhi(a.z); x0[6] = bflo(a.w); x0[7] = bfhi(a.w);
;     x1[0] = bflo(bq.x); x1[1] = bfhi(bq.x); x1[2] = bflo(bq.y); x1[3] = bfhi(bq.y); x1[4] = bflo(bq.z); x1[5] = bfhi(bq.z); x1[6] = bflo(bq.w); x1[7] = bfhi(bq.w);
;     x2[0] = bflo(c.x); x2[1] = bfhi(c.x); x2[2] = bflo(c.y); x2[3] = bfhi(c.y); x2[4] = bflo(c.z); x2[5] = bfhi(c.z); x2[6] = bflo(c.w); x2[7] = bfhi(c.w);
;   }
;   __syncthreads();
; #pragma unroll 1
;   for (int tt = 0; tt < 129; tt += 3) {
;     u32x4 r[3];
; #pragma unroll
;     for (int m = 0; m < 3; ++m) r[m] = *(const u32x4*)(xp + (size_t)(t0 + tt + m) * 1024);
; #pragma unroll
;     for (int m = 0; m < 3; ++m) {
;       float x3[8];
;       x3[0] = bflo(r[m].x); x3[1] = bfhi(r[m].x); x3[2] = bflo(r[m].y); x3[3] = bfhi(r[m].y);
;       x3[4] = bflo(r[m].z); x3[5] = bfhi(r[m].z); x3[6] = bflo(r[m].w); x3[7] = bfhi(r[m].w);
;       float y[8];
; #pragma unroll
;       for (int e = 0; e < 8; ++e) y[e] = cb[e] + cw[0][e] * x0[e] + cw[1][e] * x1[e] + cw[2][e] * x2[e] + cw[3][e] * x3[e];
;       u32x4 pk; pk.x = cvt_pk_bf16(y[0], y[1]); pk.y = cvt_pk_bf16(y[2], y[3]); pk.z = cvt_pk_bf16(y[4], y[5]); pk.w = cvt_pk_bf16(y[6], y[7]);
;       *(u32x4*)(xp + (size_t)(t0 + tt + m) * 1024) = pk;
.LBB0_1235:
	s_or_b64 exec, exec, s[4:5]
	s_lshr_b32 s4, s70, 3
	s_waitcnt vmcnt(0)
	v_lshlrev_b32_e32 v64, 16, v42
	v_and_b32_e32 v65, 0xffff0000, v42
	v_add_u32_e32 v42, 2, v54
	s_mul_i32 s92, s4, 0x204000
	v_lshlrev_b32_e32 v72, 16, v43
	v_and_b32_e32 v73, 0xffff0000, v43
	v_ashrrev_i32_e32 v43, 31, v42
	s_lshl_b32 s8, s71, 1
	s_lshl_b64 s[4:5], s[92:93], 1
	v_lshlrev_b64 v[42:43], 11, v[42:43]
	s_and_b32 s8, s8, 0x700
	v_lshl_add_u64 v[42:43], v[42:43], 0, s[4:5]
	v_lshl_or_b32 v13, v13, 1, s8
	v_or_b32_e32 v42, v42, v13
	v_lshlrev_b32_e32 v62, 16, v50
	v_and_b32_e32 v63, 0xffff0000, v50
	v_lshlrev_b32_e32 v68, 16, v51
	v_and_b32_e32 v69, 0xffff0000, v51
	v_lshl_add_u64 v[50:51], s[50:51], 0, v[42:43]
	v_add_u32_e32 v42, 1, v54
	v_ashrrev_i32_e32 v43, 31, v42
	v_lshlrev_b64 v[42:43], 11, v[42:43]
	v_lshl_add_u64 v[42:43], v[42:43], 0, s[4:5]
	v_or_b32_e32 v42, v42, v13
	v_ashrrev_i32_e32 v55, 31, v54
	v_lshlrev_b32_e32 v80, 16, v52
	v_and_b32_e32 v81, 0xffff0000, v52
	v_lshlrev_b32_e32 v66, 16, v53
	v_and_b32_e32 v67, 0xffff0000, v53
	v_lshl_add_u64 v[52:53], s[50:51], 0, v[42:43]
	v_lshlrev_b64 v[42:43], 11, v[54:55]
	v_lshl_add_u64 v[42:43], v[42:43], 0, s[4:5]
	v_or_b32_e32 v42, v42, v13
	v_lshlrev_b32_e32 v78, 16, v46
	v_and_b32_e32 v79, 0xffff0000, v46
	v_lshlrev_b32_e32 v74, 16, v47
	v_and_b32_e32 v75, 0xffff0000, v47
	v_lshlrev_b32_e32 v84, 16, v48
	v_and_b32_e32 v85, 0xffff0000, v48
	v_lshlrev_b32_e32 v82, 16, v44
	v_and_b32_e32 v83, 0xffff0000, v44
	v_lshlrev_b32_e32 v76, 16, v49
	v_and_b32_e32 v77, 0xffff0000, v49
	v_lshlrev_b32_e32 v70, 16, v45
	v_and_b32_e32 v71, 0xffff0000, v45
	v_lshl_add_u64 v[54:55], s[50:51], 0, v[42:43]
	s_mov_b32 s4, -3
	s_barrier
	v_mov_b64_e32 v[54:55], v[52:53]
	global_load_dwordx4 v[242:245], v[54:55], off offset:-2048
	global_load_dwordx4 v[246:249], v[54:55], off
	global_load_dwordx4 v[250:253], v[54:55], off offset:2048
	v_lshl_add_u64 v[54:55], v[54:55], 0, s[90:91]
	global_load_dwordx4 v[136:139], v[54:55], off offset:-2048
	global_load_dwordx4 v[140:143], v[54:55], off
	global_load_dwordx4 v[154:157], v[54:55], off offset:2048
	v_lshl_add_u64 v[54:55], v[54:55], 0, s[90:91]
	global_load_dwordx4 v[94:97], v[54:55], off offset:-2048
	global_load_dwordx4 v[98:101], v[54:55], off
	global_load_dwordx4 v[102:105], v[54:55], off offset:2048
	v_lshl_add_u64 v[54:55], v[54:55], 0, s[90:91]
	s_waitcnt vmcnt(0)
.LBB0_1236:
	s_waitcnt vmcnt(15)
	v_mov_b32_e32 v86, v242
	v_mov_b32_e32 v87, v243
	v_mov_b32_e32 v88, v244
	v_mov_b32_e32 v89, v245
	v_mov_b32_e32 v46, v246
	v_mov_b32_e32 v47, v247
	v_mov_b32_e32 v48, v248
	v_mov_b32_e32 v49, v249
	v_mov_b32_e32 v42, v250
	v_mov_b32_e32 v43, v251
	v_mov_b32_e32 v44, v252
	v_mov_b32_e32 v45, v253
	global_load_dwordx4 v[242:245], v[54:55], off offset:-2048
	global_load_dwordx4 v[246:249], v[54:55], off
	global_load_dwordx4 v[250:253], v[54:55], off offset:2048
	v_lshl_add_u64 v[54:55], v[54:55], 0, s[90:91]
	v_pk_fma_f32 v[58:59], v[14:15], v[78:79], v[4:5]
	v_pk_fma_f32 v[60:61], v[14:15], v[64:65], v[4:5]
	v_pk_fma_f32 v[58:59], v[22:23], v[64:65], v[58:59]
	v_pk_fma_f32 v[60:61], v[22:23], v[62:63], v[60:61]
	v_pk_fma_f32 v[58:59], v[30:31], v[62:63], v[58:59]
	v_pk_fma_f32 v[62:63], v[14:15], v[62:63], v[4:5]
	v_pk_fma_f32 v[74:75], v[16:17], v[74:75], v[6:7]
	v_pk_fma_f32 v[78:79], v[8:9], v[82:83], v[0:1]
	v_pk_fma_f32 v[74:75], v[24:25], v[72:73], v[74:75]
	v_pk_fma_f32 v[72:73], v[16:17], v[72:73], v[6:7]
	v_pk_fma_f32 v[74:75], v[32:33], v[68:69], v[74:75]
	v_pk_fma_f32 v[72:73], v[24:25], v[68:69], v[72:73]
	v_pk_fma_f32 v[68:69], v[16:17], v[68:69], v[6:7]
	v_pk_fma_f32 v[78:79], v[18:19], v[80:81], v[78:79]
	v_pk_fma_f32 v[76:77], v[10:11], v[76:77], v[2:3]
	s_add_i32 s4, s4, 3
	v_pk_fma_f32 v[76:77], v[20:21], v[70:71], v[76:77]
	v_pk_fma_f32 v[70:71], v[10:11], v[70:71], v[2:3]
	v_pk_fma_f32 v[76:77], v[28:29], v[66:67], v[76:77]
	v_pk_fma_f32 v[70:71], v[20:21], v[66:67], v[70:71]
	v_pk_fma_f32 v[66:67], v[10:11], v[66:67], v[2:3]
	s_cmpk_lt_u32 s4, 0x7e
	v_lshlrev_b32_e32 v56, 16, v86
	v_and_b32_e32 v57, 0xffff0000, v86
	v_pk_fma_f32 v[58:59], v[38:39], v[56:57], v[58:59]
	v_pk_fma_f32 v[60:61], v[30:31], v[56:57], v[60:61]
	v_cvt_pk_bf16_f32 v86, v58, v59
	v_lshlrev_b32_e32 v58, 16, v46
	v_and_b32_e32 v59, 0xffff0000, v46
	v_pk_fma_f32 v[60:61], v[38:39], v[58:59], v[60:61]
	v_pk_fma_f32 v[62:63], v[22:23], v[56:57], v[62:63]
	v_cvt_pk_bf16_f32 v90, v60, v61
	v_lshlrev_b32_e32 v60, 16, v42
	v_and_b32_e32 v61, 0xffff0000, v42
	v_pk_fma_f32 v[62:63], v[30:31], v[58:59], v[62:63]
	v_lshlrev_b32_e32 v46, 16, v47
	v_pk_fma_f32 v[64:65], v[38:39], v[60:61], v[62:63]
	v_lshlrev_b32_e32 v62, 16, v87
	v_and_b32_e32 v63, 0xffff0000, v87
	v_pk_fma_f32 v[74:75], v[40:41], v[62:63], v[74:75]
	v_and_b32_e32 v47, 0xffff0000, v47
	v_cvt_pk_bf16_f32 v87, v74, v75
	v_pk_fma_f32 v[72:73], v[32:33], v[62:63], v[72:73]
	v_pk_fma_f32 v[68:69], v[24:25], v[62:63], v[68:69]
	v_pk_fma_f32 v[74:75], v[8:9], v[84:85], v[0:1]
	v_pk_fma_f32 v[72:73], v[40:41], v[46:47], v[72:73]
	v_lshlrev_b32_e32 v42, 16, v43
	v_and_b32_e32 v43, 0xffff0000, v43
	v_pk_fma_f32 v[68:69], v[32:33], v[46:47], v[68:69]
	v_pk_fma_f32 v[74:75], v[18:19], v[82:83], v[74:75]
	v_cvt_pk_bf16_f32 v91, v72, v73
	v_pk_fma_f32 v[72:73], v[40:41], v[42:43], v[68:69]
	v_lshlrev_b32_e32 v68, 16, v88
	v_and_b32_e32 v69, 0xffff0000, v88
	v_pk_fma_f32 v[74:75], v[26:27], v[80:81], v[74:75]
	v_pk_fma_f32 v[78:79], v[26:27], v[68:69], v[78:79]
	v_pk_fma_f32 v[74:75], v[34:35], v[68:69], v[74:75]
	v_pk_fma_f32 v[80:81], v[8:9], v[80:81], v[0:1]
	v_cvt_pk_bf16_f32 v88, v74, v75
	v_lshlrev_b32_e32 v74, 16, v48
; __device__ __forceinline__ float bflo(unsigned v) { return __uint_as_float(v << 16); }
; __device__ __forceinline__ float bfhi(unsigned v) { return __uint_as_float(v & 0xffff0000u); }
; __device__ __forceinline__ void conv_unit(const Params& p, const WS& ws, int j, int u) {
;     ...
; #pragma unroll 1
;   for (int tt = 0; tt < 129; tt += 3) {
;     u32x4 r[3];
; #pragma unroll
;     for (int m = 0; m < 3; ++m) r[m] = *(const u32x4*)(xp + (size_t)(t0 + tt + m) * 1024);
; #pragma unroll
;     for (int m = 0; m < 3; ++m) {
;       float x3[8];
;       x3[0] = bflo(r[m].x); x3[1] = bfhi(r[m].x); x3[2] = bflo(r[m].y); x3[3] = bfhi(r[m].y);
;       x3[4] = bflo(r[m].z); x3[5] = bfhi(r[m].z); x3[6] = bflo(r[m].w); x3[7] = bfhi(r[m].w);
;       float y[8];
; #pragma unroll
;       for (int e = 0; e < 8; ++e) y[e] = cb[e] + cw[0][e] * x0[e] + cw[1][e] * x1[e] + cw[2][e] * x2[e] + cw[3][e] * x3[e];
;       u32x4 pk; pk.x = cvt_pk_bf16(y[0], y[1]); pk.y = cvt_pk_bf16(y[2], y[3]); pk.z = cvt_pk_bf16(y[4], y[5]); pk.w = cvt_pk_bf16(y[6], y[7]);
;       *(u32x4*)(xp + (size_t)(t0 + tt + m) * 1024) = pk;
; #pragma unroll
;       for (int e = 0; e < 8; ++e) { x0[e] = x1[e]; x1[e] = x2[e]; x2[e] = x3[e]; }
;     }
;   }
	v_and_b32_e32 v75, 0xffff0000, v48
	v_pk_fma_f32 v[78:79], v[34:35], v[74:75], v[78:79]
	v_pk_fma_f32 v[80:81], v[18:19], v[68:69], v[80:81]
	v_cvt_pk_bf16_f32 v92, v78, v79
	v_lshlrev_b32_e32 v78, 16, v44
	v_and_b32_e32 v79, 0xffff0000, v44
	v_pk_fma_f32 v[80:81], v[26:27], v[74:75], v[80:81]
	v_lshlrev_b32_e32 v48, 16, v49
	v_pk_fma_f32 v[82:83], v[34:35], v[78:79], v[80:81]
	v_lshlrev_b32_e32 v80, 16, v89
	v_and_b32_e32 v81, 0xffff0000, v89
	v_and_b32_e32 v49, 0xffff0000, v49
	v_pk_fma_f32 v[70:71], v[28:29], v[80:81], v[70:71]
	v_pk_fma_f32 v[66:67], v[20:21], v[80:81], v[66:67]
	v_pk_fma_f32 v[70:71], v[36:37], v[48:49], v[70:71]
	v_lshlrev_b32_e32 v44, 16, v45
	v_and_b32_e32 v45, 0xffff0000, v45
	v_pk_fma_f32 v[66:67], v[28:29], v[48:49], v[66:67]
	v_pk_fma_f32 v[76:77], v[36:37], v[80:81], v[76:77]
	v_cvt_pk_bf16_f32 v93, v70, v71
	v_pk_fma_f32 v[70:71], v[36:37], v[44:45], v[66:67]
	v_cvt_pk_bf16_f32 v89, v76, v77
	v_cvt_pk_bf16_f32 v64, v64, v65
	v_cvt_pk_bf16_f32 v65, v72, v73
	v_cvt_pk_bf16_f32 v66, v82, v83
	v_cvt_pk_bf16_f32 v67, v70, v71
	global_store_dwordx4 v[52:53], v[86:89], off offset:-2048
	global_store_dwordx4 v[52:53], v[90:93], off
	global_store_dwordx4 v[52:53], v[64:67], off offset:2048
	s_nop 2
	v_lshl_add_u64 v[52:53], v[52:53], 0, s[90:91]
	v_mov_b64_e32 v[66:67], v[44:45]
	v_mov_b64_e32 v[70:71], v[48:49]
	v_mov_b64_e32 v[76:77], v[80:81]
	v_mov_b64_e32 v[84:85], v[68:69]
	v_mov_b64_e32 v[82:83], v[74:75]
	v_mov_b64_e32 v[80:81], v[78:79]
	v_mov_b64_e32 v[74:75], v[62:63]
	v_mov_b64_e32 v[72:73], v[46:47]
	v_mov_b64_e32 v[68:69], v[42:43]
	v_mov_b64_e32 v[78:79], v[56:57]
	v_mov_b64_e32 v[64:65], v[58:59]
	v_mov_b64_e32 v[62:63], v[60:61]
	s_cbranch_scc0 .Lconv_exit
.Lconv_u1:
	s_waitcnt vmcnt(15)
	v_mov_b32_e32 v86, v136
	v_mov_b32_e32 v87, v137
	v_mov_b32_e32 v88, v138
	v_mov_b32_e32 v89, v139
	v_mov_b32_e32 v46, v140
	v_mov_b32_e32 v47, v141
	v_mov_b32_e32 v48, v142
	v_mov_b32_e32 v49, v143
	v_mov_b32_e32 v42, v154
	v_mov_b32_e32 v43, v155
	v_mov_b32_e32 v44, v156
	v_mov_b32_e32 v45, v157
	global_load_dwordx4 v[136:139], v[54:55], off offset:-2048
	global_load_dwordx4 v[140:143], v[54:55], off
	global_load_dwordx4 v[154:157], v[54:55], off offset:2048
	v_lshl_add_u64 v[54:55], v[54:55], 0, s[90:91]
	v_pk_fma_f32 v[58:59], v[14:15], v[78:79], v[4:5]
	v_pk_fma_f32 v[60:61], v[14:15], v[64:65], v[4:5]
	v_pk_fma_f32 v[58:59], v[22:23], v[64:65], v[58:59]
	v_pk_fma_f32 v[60:61], v[22:23], v[62:63], v[60:61]
	v_pk_fma_f32 v[58:59], v[30:31], v[62:63], v[58:59]
	v_pk_fma_f32 v[62:63], v[14:15], v[62:63], v[4:5]
	v_pk_fma_f32 v[74:75], v[16:17], v[74:75], v[6:7]
	v_pk_fma_f32 v[78:79], v[8:9], v[82:83], v[0:1]
	v_pk_fma_f32 v[74:75], v[24:25], v[72:73], v[74:75]
	v_pk_fma_f32 v[72:73], v[16:17], v[72:73], v[6:7]
	v_pk_fma_f32 v[74:75], v[32:33], v[68:69], v[74:75]
	v_pk_fma_f32 v[72:73], v[24:25], v[68:69], v[72:73]
	v_pk_fma_f32 v[68:69], v[16:17], v[68:69], v[6:7]
	v_pk_fma_f32 v[78:79], v[18:19], v[80:81], v[78:79]
	v_pk_fma_f32 v[76:77], v[10:11], v[76:77], v[2:3]
	s_add_i32 s4, s4, 3
	v_pk_fma_f32 v[76:77], v[20:21], v[70:71], v[76:77]
	v_pk_fma_f32 v[70:71], v[10:11], v[70:71], v[2:3]
	v_pk_fma_f32 v[76:77], v[28:29], v[66:67], v[76:77]
	v_pk_fma_f32 v[70:71], v[20:21], v[66:67], v[70:71]
	v_pk_fma_f32 v[66:67], v[10:11], v[66:67], v[2:3]
	s_cmpk_lt_u32 s4, 0x7e
	v_lshlrev_b32_e32 v56, 16, v86
	v_and_b32_e32 v57, 0xffff0000, v86
	v_pk_fma_f32 v[58:59], v[38:39], v[56:57], v[58:59]
	v_pk_fma_f32 v[60:61], v[30:31], v[56:57], v[60:61]
	v_cvt_pk_bf16_f32 v86, v58, v59
	v_lshlrev_b32_e32 v58, 16, v46
	v_and_b32_e32 v59, 0xffff0000, v46
	v_pk_fma_f32 v[60:61], v[38:39], v[58:59], v[60:61]
	v_pk_fma_f32 v[62:63], v[22:23], v[56:57], v[62:63]
	v_cvt_pk_bf16_f32 v90, v60, v61
	v_lshlrev_b32_e32 v60, 16, v42
	v_and_b32_e32 v61, 0xffff0000, v42
	v_pk_fma_f32 v[62:63], v[30:31], v[58:59], v[62:63]
	v_lshlrev_b32_e32 v46, 16, v47
	v_pk_fma_f32 v[64:65], v[38:39], v[60:61], v[62:63]
	v_lshlrev_b32_e32 v62, 16, v87
	v_and_b32_e32 v63, 0xffff0000, v87
	v_pk_fma_f32 v[74:75], v[40:41], v[62:63], v[74:75]
	v_and_b32_e32 v47, 0xffff0000, v47
	v_cvt_pk_bf16_f32 v87, v74, v75
	v_pk_fma_f32 v[72:73], v[32:33], v[62:63], v[72:73]
	v_pk_fma_f32 v[68:69], v[24:25], v[62:63], v[68:69]
	v_pk_fma_f32 v[74:75], v[8:9], v[84:85], v[0:1]
	v_pk_fma_f32 v[72:73], v[40:41], v[46:47], v[72:73]
	v_lshlrev_b32_e32 v42, 16, v43
	v_and_b32_e32 v43, 0xffff0000, v43
	v_pk_fma_f32 v[68:69], v[32:33], v[46:47], v[68:69]
	v_pk_fma_f32 v[74:75], v[18:19], v[82:83], v[74:75]
	v_cvt_pk_bf16_f32 v91, v72, v73
	v_pk_fma_f32 v[72:73], v[40:41], v[42:43], v[68:69]
	v_lshlrev_b32_e32 v68, 16, v88
	v_and_b32_e32 v69, 0xffff0000, v88
	v_pk_fma_f32 v[74:75], v[26:27], v[80:81], v[74:75]
	v_pk_fma_f32 v[78:79], v[26:27], v[68:69], v[78:79]
	v_pk_fma_f32 v[74:75], v[34:35], v[68:69], v[74:75]
	v_pk_fma_f32 v[80:81], v[8:9], v[80:81], v[0:1]
	v_cvt_pk_bf16_f32 v88, v74, v75
	v_lshlrev_b32_e32 v74, 16, v48
	v_and_b32_e32 v75, 0xffff0000, v48
	v_pk_fma_f32 v[78:79], v[34:35], v[74:75], v[78:79]
	v_pk_fma_f32 v[80:81], v[18:19], v[68:69], v[80:81]
	v_cvt_pk_bf16_f32 v92, v78, v79
	v_lshlrev_b32_e32 v78, 16, v44
	v_and_b32_e32 v79, 0xffff0000, v44
	v_pk_fma_f32 v[80:81], v[26:27], v[74:75], v[80:81]
	v_lshlrev_b32_e32 v48, 16, v49
	v_pk_fma_f32 v[82:83], v[34:35], v[78:79], v[80:81]
	v_lshlrev_b32_e32 v80, 16, v89
	v_and_b32_e32 v81, 0xffff0000, v89
	v_and_b32_e32 v49, 0xffff0000, v49
	v_pk_fma_f32 v[70:71], v[28:29], v[80:81], v[70:71]
	v_pk_fma_f32 v[66:67], v[20:21], v[80:81], v[66:67]
	v_pk_fma_f32 v[70:71], v[36:37], v[48:49], v[70:71]
	v_lshlrev_b32_e32 v44, 16, v45
	v_and_b32_e32 v45, 0xffff0000, v45
	v_pk_fma_f32 v[66:67], v[28:29], v[48:49], v[66:67]
	v_pk_fma_f32 v[76:77], v[36:37], v[80:81], v[76:77]
	v_cvt_pk_bf16_f32 v93, v70, v71
	v_pk_fma_f32 v[70:71], v[36:37], v[44:45], v[66:67]
	v_cvt_pk_bf16_f32 v89, v76, v77
	v_cvt_pk_bf16_f32 v64, v64, v65
	v_cvt_pk_bf16_f32 v65, v72, v73
	v_cvt_pk_bf16_f32 v66, v82, v83
	v_cvt_pk_bf16_f32 v67, v70, v71
	global_store_dwordx4 v[52:53], v[86:89], off offset:-2048
	global_store_dwordx4 v[52:53], v[90:93], off
	global_store_dwordx4 v[52:53], v[64:67], off offset:2048
	s_nop 2
	v_lshl_add_u64 v[52:53], v[52:53], 0, s[90:91]
	v_mov_b64_e32 v[66:67], v[44:45]
	v_mov_b64_e32 v[70:71], v[48:49]
	v_mov_b64_e32 v[76:77], v[80:81]
	v_mov_b64_e32 v[84:85], v[68:69]
	v_mov_b64_e32 v[82:83], v[74:75]
	v_mov_b64_e32 v[80:81], v[78:79]
	v_mov_b64_e32 v[74:75], v[62:63]
	v_mov_b64_e32 v[72:73], v[46:47]
	v_mov_b64_e32 v[68:69], v[42:43]
	v_mov_b64_e32 v[78:79], v[56:57]
	v_mov_b64_e32 v[64:65], v[58:59]
	v_mov_b64_e32 v[62:63], v[60:61]
	s_cbranch_scc0 .Lconv_exit
; __device__ __forceinline__ float bflo(unsigned v) { return __uint_as_float(v << 16); }
; __device__ __forceinline__ float bfhi(unsigned v) { return __uint_as_float(v & 0xffff0000u); }
; __device__ __forceinline__ void conv_unit(const Params& p, const WS& ws, int j, int u) {
;     ...
; #pragma unroll 1
;   for (int tt = 0; tt < 129; tt += 3) {
;     u32x4 r[3];
; #pragma unroll
;     for (int m = 0; m < 3; ++m) r[m] = *(const u32x4*)(xp + (size_t)(t0 + tt + m) * 1024);
; #pragma unroll
;     for (int m = 0; m < 3; ++m) {
;       float x3[8];
;       x3[0] = bflo(r[m].x); x3[1] = bfhi(r[m].x); x3[2] = bflo(r[m].y); x3[3] = bfhi(r[m].y);
;       x3[4] = bflo(r[m].z); x3[5] = bfhi(r[m].z); x3[6] = bflo(r[m].w); x3[7] = bfhi(r[m].w);
;       float y[8];
; #pragma unroll
;       for (int e = 0; e < 8; ++e) y[e] = cb[e] + cw[0][e] * x0[e] + cw[1][e] * x1[e] + cw[2][e] * x2[e] + cw[3][e] * x3[e];
;       u32x4 pk; pk.x = cvt_pk_bf16(y[0], y[1]); pk.y = cvt_pk_bf16(y[2], y[3]); pk.z = cvt_pk_bf16(y[4], y[5]); pk.w = cvt_pk_bf16(y[6], y[7]);
;       *(u32x4*)(xp + (size_t)(t0 + tt + m) * 1024) = pk;
; #pragma unroll
;       for (int e = 0; e < 8; ++e) { x0[e] = x1[e]; x1[e] = x2[e]; x2[e] = x3[e]; }
;     }
;   }
;   __syncthreads();
.Lconv_u2:
	s_waitcnt vmcnt(15)
	v_mov_b32_e32 v86, v94
	v_mov_b32_e32 v87, v95
	v_mov_b32_e32 v88, v96
	v_mov_b32_e32 v89, v97
	v_mov_b32_e32 v46, v98
	v_mov_b32_e32 v47, v99
	v_mov_b32_e32 v48, v100
	v_mov_b32_e32 v49, v101
	v_mov_b32_e32 v42, v102
	v_mov_b32_e32 v43, v103
	v_mov_b32_e32 v44, v104
	v_mov_b32_e32 v45, v105
	global_load_dwordx4 v[94:97], v[54:55], off offset:-2048
	global_load_dwordx4 v[98:101], v[54:55], off
	global_load_dwordx4 v[102:105], v[54:55], off offset:2048
	v_lshl_add_u64 v[54:55], v[54:55], 0, s[90:91]
	v_pk_fma_f32 v[58:59], v[14:15], v[78:79], v[4:5]
	v_pk_fma_f32 v[60:61], v[14:15], v[64:65], v[4:5]
	v_pk_fma_f32 v[58:59], v[22:23], v[64:65], v[58:59]
	v_pk_fma_f32 v[60:61], v[22:23], v[62:63], v[60:61]
	v_pk_fma_f32 v[58:59], v[30:31], v[62:63], v[58:59]
	v_pk_fma_f32 v[62:63], v[14:15], v[62:63], v[4:5]
	v_pk_fma_f32 v[74:75], v[16:17], v[74:75], v[6:7]
	v_pk_fma_f32 v[78:79], v[8:9], v[82:83], v[0:1]
	v_pk_fma_f32 v[74:75], v[24:25], v[72:73], v[74:75]
	v_pk_fma_f32 v[72:73], v[16:17], v[72:73], v[6:7]
	v_pk_fma_f32 v[74:75], v[32:33], v[68:69], v[74:75]
	v_pk_fma_f32 v[72:73], v[24:25], v[68:69], v[72:73]
	v_pk_fma_f32 v[68:69], v[16:17], v[68:69], v[6:7]
	v_pk_fma_f32 v[78:79], v[18:19], v[80:81], v[78:79]
	v_pk_fma_f32 v[76:77], v[10:11], v[76:77], v[2:3]
	s_add_i32 s4, s4, 3
	v_pk_fma_f32 v[76:77], v[20:21], v[70:71], v[76:77]
	v_pk_fma_f32 v[70:71], v[10:11], v[70:71], v[2:3]
	v_pk_fma_f32 v[76:77], v[28:29], v[66:67], v[76:77]
	v_pk_fma_f32 v[70:71], v[20:21], v[66:67], v[70:71]
	v_pk_fma_f32 v[66:67], v[10:11], v[66:67], v[2:3]
	s_cmpk_lt_u32 s4, 0x7e
	v_lshlrev_b32_e32 v56, 16, v86
	v_and_b32_e32 v57, 0xffff0000, v86
	v_pk_fma_f32 v[58:59], v[38:39], v[56:57], v[58:59]
	v_pk_fma_f32 v[60:61], v[30:31], v[56:57], v[60:61]
	v_cvt_pk_bf16_f32 v86, v58, v59
	v_lshlrev_b32_e32 v58, 16, v46
	v_and_b32_e32 v59, 0xffff0000, v46
	v_pk_fma_f32 v[60:61], v[38:39], v[58:59], v[60:61]
	v_pk_fma_f32 v[62:63], v[22:23], v[56:57], v[62:63]
	v_cvt_pk_bf16_f32 v90, v60, v61
	v_lshlrev_b32_e32 v60, 16, v42
	v_and_b32_e32 v61, 0xffff0000, v42
	v_pk_fma_f32 v[62:63], v[30:31], v[58:59], v[62:63]
	v_lshlrev_b32_e32 v46, 16, v47
	v_pk_fma_f32 v[64:65], v[38:39], v[60:61], v[62:63]
	v_lshlrev_b32_e32 v62, 16, v87
	v_and_b32_e32 v63, 0xffff0000, v87
	v_pk_fma_f32 v[74:75], v[40:41], v[62:63], v[74:75]
	v_and_b32_e32 v47, 0xffff0000, v47
	v_cvt_pk_bf16_f32 v87, v74, v75
	v_pk_fma_f32 v[72:73], v[32:33], v[62:63], v[72:73]
	v_pk_fma_f32 v[68:69], v[24:25], v[62:63], v[68:69]
	v_pk_fma_f32 v[74:75], v[8:9], v[84:85], v[0:1]
	v_pk_fma_f32 v[72:73], v[40:41], v[46:47], v[72:73]
	v_lshlrev_b32_e32 v42, 16, v43
	v_and_b32_e32 v43, 0xffff0000, v43
	v_pk_fma_f32 v[68:69], v[32:33], v[46:47], v[68:69]
	v_pk_fma_f32 v[74:75], v[18:19], v[82:83], v[74:75]
	v_cvt_pk_bf16_f32 v91, v72, v73
	v_pk_fma_f32 v[72:73], v[40:41], v[42:43], v[68:69]
	v_lshlrev_b32_e32 v68, 16, v88
	v_and_b32_e32 v69, 0xffff0000, v88
	v_pk_fma_f32 v[74:75], v[26:27], v[80:81], v[74:75]
	v_pk_fma_f32 v[78:79], v[26:27], v[68:69], v[78:79]
	v_pk_fma_f32 v[74:75], v[34:35], v[68:69], v[74:75]
	v_pk_fma_f32 v[80:81], v[8:9], v[80:81], v[0:1]
	v_cvt_pk_bf16_f32 v88, v74, v75
	v_lshlrev_b32_e32 v74, 16, v48
	v_and_b32_e32 v75, 0xffff0000, v48
	v_pk_fma_f32 v[78:79], v[34:35], v[74:75], v[78:79]
	v_pk_fma_f32 v[80:81], v[18:19], v[68:69], v[80:81]
	v_cvt_pk_bf16_f32 v92, v78, v79
	v_lshlrev_b32_e32 v78, 16, v44
	v_and_b32_e32 v79, 0xffff0000, v44
	v_pk_fma_f32 v[80:81], v[26:27], v[74:75], v[80:81]
	v_lshlrev_b32_e32 v48, 16, v49
	v_pk_fma_f32 v[82:83], v[34:35], v[78:79], v[80:81]
	v_lshlrev_b32_e32 v80, 16, v89
	v_and_b32_e32 v81, 0xffff0000, v89
	v_and_b32_e32 v49, 0xffff0000, v49
	v_pk_fma_f32 v[70:71], v[28:29], v[80:81], v[70:71]
	v_pk_fma_f32 v[66:67], v[20:21], v[80:81], v[66:67]
	v_pk_fma_f32 v[70:71], v[36:37], v[48:49], v[70:71]
	v_lshlrev_b32_e32 v44, 16, v45
	v_and_b32_e32 v45, 0xffff0000, v45
	v_pk_fma_f32 v[66:67], v[28:29], v[48:49], v[66:67]
	v_pk_fma_f32 v[76:77], v[36:37], v[80:81], v[76:77]
	v_cvt_pk_bf16_f32 v93, v70, v71
	v_pk_fma_f32 v[70:71], v[36:37], v[44:45], v[66:67]
	v_cvt_pk_bf16_f32 v89, v76, v77
	v_cvt_pk_bf16_f32 v64, v64, v65
	v_cvt_pk_bf16_f32 v65, v72, v73
	v_cvt_pk_bf16_f32 v66, v82, v83
	v_cvt_pk_bf16_f32 v67, v70, v71
	global_store_dwordx4 v[52:53], v[86:89], off offset:-2048
	global_store_dwordx4 v[52:53], v[90:93], off
	global_store_dwordx4 v[52:53], v[64:67], off offset:2048
	s_nop 2
	v_lshl_add_u64 v[52:53], v[52:53], 0, s[90:91]
	v_mov_b64_e32 v[66:67], v[44:45]
	v_mov_b64_e32 v[70:71], v[48:49]
	v_mov_b64_e32 v[76:77], v[80:81]
	v_mov_b64_e32 v[84:85], v[68:69]
	v_mov_b64_e32 v[82:83], v[74:75]
	v_mov_b64_e32 v[80:81], v[78:79]
	v_mov_b64_e32 v[74:75], v[62:63]
	v_mov_b64_e32 v[72:73], v[46:47]
	v_mov_b64_e32 v[68:69], v[42:43]
	v_mov_b64_e32 v[78:79], v[56:57]
	v_mov_b64_e32 v[64:65], v[58:59]
	v_mov_b64_e32 v[62:63], v[60:61]
	s_cbranch_scc1 .LBB0_1236
.Lconv_exit:
	s_barrier
	s_mov_b64 s[4:5], 0
